# panel-wait relaxation (P3->P4a poll deferred to P4a sub-unit 1; P4b walks its own K columns first, poll before the K-loop) with padding so every hot loop keeps its baseline byte phase; on top of barri
# speedup vs baseline: 1.0108x; 1.0081x over previous
_ZN2mk6mk_fwdENS_4ArgsE:
	s_lshr_b32 s101, s2, 3
	s_and_b32 s101, s101, 7
	s_lshl_b32 s101, s101, 8
	v_lshl_add_u32 v1, v0, 2, 0
	v_add_u32_e32 v1, 0x20000, v1
	v_mov_b32_e32 v2, 0
	s_mov_b32 s72, s2
	s_mov_b64 s[74:75], s[0:1]
	ds_write2st64_b32 v1, v2, v2 offset1:8
	ds_write2st64_b32 v1, v2, v2 offset0:16 offset1:24
	v_or_b32_e32 v1, 0x800, v0
	s_mov_b64 s[0:1], -1
	s_and_saveexec_b64 s[2:3], s[0:1]
	v_lshl_add_u32 v3, v1, 2, 0
	v_add_u32_e32 v3, 0x20000, v3
	ds_write_b32 v3, v2
	s_or_b64 exec, exec, s[2:3]
	s_and_saveexec_b64 s[2:3], s[0:1]
	s_add_i32 s0, 0, 0x20000
	v_lshl_add_u32 v1, v1, 2, s0
	v_mov_b32_e32 v2, 0
	ds_write_b32 v1, v2 offset:2048
	s_or_b64 exec, exec, s[2:3]
	v_or_b32_e32 v1, 0xc00, v0
	v_cmp_gt_u32_e64 s[0:1], 7, 6
	v_cmp_gt_u32_e64 s[4:5], 7, 5
	s_and_saveexec_b64 s[2:3], s[4:5]
	v_lshl_add_u32 v2, v1, 2, 0
	v_add_u32_e32 v2, 0x20000, v2
	v_mov_b32_e32 v3, 0
	ds_write_b32 v2, v3
	s_or_b64 exec, exec, s[2:3]
	s_and_saveexec_b64 s[2:3], s[0:1]
	s_add_i32 s0, 0, 0x20000
	v_lshl_add_u32 v1, v1, 2, s0
	v_mov_b32_e32 v2, 0
	ds_write_b32 v1, v2 offset:2048
	s_or_b64 exec, exec, s[2:3]
	v_and_b32_e32 v1, 63, v0
	v_cmp_eq_u32_e32 vcc, 0, v1
	s_waitcnt lgkmcnt(0)
	s_barrier
	s_and_saveexec_b64 s[0:1], vcc
	s_cbranch_execz .LBB0_10
	s_getreg_b32 s2, hwreg(HW_REG_HW_ID, 0, 6)
	s_lshl_b32 s2, s2, 2
	s_and_b32 s2, s2, 0xfc
	s_add_i32 s2, s2, 0
	s_add_i32 s2, s2, 0x20200
	v_lshrrev_b32_e32 v1, 6, v0
	v_mov_b32_e32 v2, s2
	ds_write_b32 v2, v1

.LBB0_898:
	s_mov_b64 s[2:3], s[74:75]
	s_waitcnt vmcnt(0)
	s_barrier
	s_getreg_b32 s0, hwreg(HW_REG_HW_ID, 0, 6)
	s_lshl_b32 s0, s0, 2
	s_and_b32 s0, s0, 0xfc
	s_add_i32 s0, s0, 0
	s_add_i32 s0, s0, 0x20200
	v_mov_b32_e32 v0, s0
	ds_read_b32 v0, v0
	v_readlane_b32 s0, v253, 12
	v_readlane_b32 s1, v253, 13
	s_add_i32 s0, s68, s0
	v_mbcnt_lo_u32_b32 v1, -1, 0
	v_mbcnt_hi_u32_b32 v1, -1, v1
	s_waitcnt lgkmcnt(0)
	v_readfirstlane_b32 s4, v0
	s_lshl_b32 s4, s4, 6
	v_sub_u32_e32 v0, 0, v1
	s_ashr_i32 s1, s0, 31
	s_lshl_b32 s100, s0, 2
	s_add_u32 s100, s100, 0xb400
	v_cmp_eq_u32_e32 vcc, s4, v0
	s_and_saveexec_b64 s[4:5], vcc
	s_cbranch_execz .LBB0_901
	s_mov_b64 s[8:9], exec
	v_mbcnt_lo_u32_b32 v0, s8, 0
	v_mbcnt_hi_u32_b32 v0, s9, v0
	v_cmp_eq_u32_e32 vcc, 0, v0
	s_and_b64 s[10:11], exec, vcc
	s_mov_b64 exec, s[10:11]
	s_cbranch_execz .LBB0_901
	s_load_dwordx2 s[2:3], s[2:3], 0xf8
	s_lshl_b64 s[10:11], s[0:1], 2
	v_mov_b32_e32 v1, 0xb000
	s_waitcnt lgkmcnt(0)
	s_add_u32 s2, s2, s10
	s_addc_u32 s3, s3, s11
	s_bcnt1_i32_b64 s8, s[8:9]
	v_mov_b32_e32 v0, s8
	global_atomic_add v1, v0, s[2:3] offset:1024
.LBB0_901:
	s_or_b64 exec, exec, s[4:5]
	s_mov_b64 s[4:5], s[74:75]
	s_getreg_b32 s2, hwreg(HW_REG_HW_ID, 0, 6)
	s_lshl_b32 s2, s2, 2
	s_and_b32 s2, s2, 0xfc
	s_add_i32 s2, s2, 0
	s_add_i32 s2, s2, 0x20200
	v_mov_b32_e32 v0, s2
	ds_read_b32 v0, v0
	v_mbcnt_lo_u32_b32 v1, -1, 0
	v_mbcnt_hi_u32_b32 v1, -1, v1
	s_waitcnt lgkmcnt(0)
	v_readfirstlane_b32 s2, v0
	s_lshl_b32 s2, s2, 6
	v_sub_u32_e32 v0, 0, v1
	v_cmp_eq_u32_e32 vcc, s2, v0
	s_and_saveexec_b64 s[2:3], vcc
	s_branch .LBB0_914
	s_nop 0
	s_nop 0
	s_nop 0
	s_nop 0
	s_nop 0
	s_nop 0
	s_nop 0
	s_nop 0
	s_nop 0
	s_nop 0
	s_nop 0
	s_nop 0
	s_nop 0
	s_nop 0
	s_nop 0
	s_nop 0
	s_nop 0
	s_nop 0
	s_nop 0
	s_nop 0
	s_nop 0
	s_nop 0
	s_nop 0
	s_nop 0
	s_nop 0
	s_nop 0
	s_nop 0
	s_nop 0
	s_nop 0
	s_nop 0
	s_nop 0
	s_nop 0
	s_nop 0
	s_nop 0
	s_nop 0
	s_nop 0
	s_nop 0
	s_nop 0
	s_nop 0
	s_nop 0
	s_nop 0
	s_nop 0
	s_nop 0
	s_nop 0
	s_nop 0
	s_nop 0
	s_nop 0
	s_nop 0
	s_nop 0
	s_nop 0
	s_nop 0
	s_nop 0
	s_nop 0
	s_nop 0
	s_nop 0
	s_nop 0
	s_nop 0
	s_nop 0
	s_nop 0
	s_nop 0
	s_nop 0
	s_nop 0
	s_nop 0
	s_nop 0
	s_nop 0
	s_nop 0
	s_nop 0
	s_nop 0
	s_nop 0
	s_nop 0
	s_nop 0
	s_nop 0
	s_nop 0
	s_nop 0

.LBB0_924:
	s_cmp_lg_u32 s43, 1
	s_cbranch_scc1 .Lmy_pw1_a
	s_cmp_lg_u32 s30, 0
	s_cbranch_scc1 .Lmy_pw1_a
	s_load_dwordx2 vcc, s[74:75], 0xf8
	s_waitcnt lgkmcnt(0)
	s_add_u32 vcc_lo, vcc_lo, s100
	s_addc_u32 vcc_hi, vcc_hi, 0
	global_load_dword v174, v137, vcc sc1

.Lmy_pw1_chk:
	v_cmp_lt_u32_e32 vcc, 7, v174
	s_cbranch_vccnz .Lmy_pw1_ok
	s_sleep 1
	s_load_dwordx2 vcc, s[74:75], 0xf8
	s_waitcnt lgkmcnt(0)
	s_add_u32 vcc_lo, vcc_lo, s100
	s_addc_u32 vcc_hi, vcc_hi, 0
	global_load_dword v174, v137, vcc sc1
	s_waitcnt vmcnt(0)
	s_branch .Lmy_pw1_chk

.Lmy_pw1_done:
	s_nop 0
	s_nop 0
	v_lshlrev_b32_e32 v138, 16, v1
	v_and_b32_e32 v139, 0xffff0000, v1
	s_cmp_lt_u32 s46, 8
	v_pk_mul_f32 v[178:179], v[94:95], v[138:139]
	v_pk_fma_f32 v[94:95], v[94:95], v[138:139], v[170:171]
	v_lshlrev_b32_e32 v138, 16, v0
	v_and_b32_e32 v139, 0xffff0000, v0
	v_lshlrev_b32_e32 v170, 16, v2
	v_and_b32_e32 v171, 0xffff0000, v2
	v_lshlrev_b32_e32 v180, 16, v3
	v_and_b32_e32 v181, 0xffff0000, v3
	v_lshl_add_u32 v174, v136, 3, s8
	s_cselect_b64 s[8:9], -1, 0
	s_cmp_eq_u32 s15, 3
	v_pk_mul_f32 v[182:183], v[92:93], v[138:139]
	v_pk_mul_f32 v[184:185], v[88:89], v[170:171]
	v_pk_mul_f32 v[186:187], v[90:91], v[180:181]
	v_pk_fma_f32 v[92:93], v[92:93], v[138:139], v[168:169]
	v_pk_fma_f32 v[88:89], v[88:89], v[170:171], v[166:167]
	v_pk_fma_f32 v[90:91], v[90:91], v[180:181], v[162:163]
	s_cselect_b64 s[22:23], -1, 0
	s_cmp_lg_u32 s15, 3
	v_cndmask_b32_e64 v171, v95, v179, s[8:9]
	v_cndmask_b32_e64 v170, v94, v178, s[8:9]
	v_cndmask_b32_e64 v169, v93, v183, s[8:9]
	v_cndmask_b32_e64 v168, v92, v182, s[8:9]
	v_cndmask_b32_e64 v163, v91, v187, s[8:9]
	v_cndmask_b32_e64 v162, v90, v186, s[8:9]
	v_cndmask_b32_e64 v167, v89, v185, s[8:9]
	v_cndmask_b32_e64 v166, v88, v184, s[8:9]
	v_lshlrev_b32_e32 v88, 1, v174
	s_cbranch_scc1 .LBB0_926
	v_cvt_pk_bf16_f32 v90, v168, v169
	v_cvt_pk_bf16_f32 v91, v170, v171
	v_cvt_pk_bf16_f32 v92, v166, v167
	v_cvt_pk_bf16_f32 v93, v162, v163
	v_lshl_add_u32 v89, v172, 11, v88
	buffer_store_dwordx4 v[90:93], v89, s[84:87], 0 offen sc1

.LBB0_949:
	s_or_b64 exec, exec, s[4:5]
	s_mov_b64 s[4:5], s[74:75]
	s_getreg_b32 s2, hwreg(HW_REG_HW_ID, 0, 6)
	s_lshl_b32 s2, s2, 2
	s_and_b32 s2, s2, 0xfc
	s_add_i32 s2, s2, 0
	s_add_i32 s2, s2, 0x20200
	v_mov_b32_e32 v0, s2
	ds_read_b32 v0, v0
	v_mbcnt_lo_u32_b32 v1, -1, 0
	v_mbcnt_hi_u32_b32 v1, -1, v1
	s_waitcnt lgkmcnt(0)
	v_readfirstlane_b32 s2, v0
	s_lshl_b32 s2, s2, 6
	v_sub_u32_e32 v0, 0, v1
	v_cmp_eq_u32_e32 vcc, s2, v0
	s_and_saveexec_b64 s[2:3], vcc
	s_branch .LBB0_962
	s_nop 0
	s_nop 0
	s_nop 0
	s_nop 0
	s_nop 0
	s_nop 0
	s_nop 0
	s_nop 0
	s_nop 0
	s_nop 0
	s_nop 0
	s_nop 0
	s_nop 0
	s_nop 0

.LBB0_1027:
	v_ashrrev_i32_e32 v25, 31, v30
	v_lshrrev_b32_e32 v25, 26, v25
	v_add_u32_e32 v25, v30, v25
	v_ashrrev_i32_e32 v57, 6, v25
	v_bfe_i32 v25, v30, 27, 1
	v_lshlrev_b32_e32 v24, 4, v30
	v_lshrrev_b32_e32 v25, 22, v25
	v_add_u32_e32 v25, v24, v25
	v_and_b32_e32 v25, 0xfffffc00, v25
	v_sub_u32_e32 v25, v24, v25
	v_lshrrev_b32_e32 v30, 4, v25
	s_lshl_b64 s[14:15], s[40:41], 21
	v_bitop3_b32 v25, v30, v25, 32 bitop3:0x6c
	s_add_u32 s12, s2, s14
	v_ashrrev_i32_e32 v31, 31, v25
	s_addc_u32 s13, s3, s15
	v_readlane_b32 s6, v253, 27
	v_lshrrev_b32_e32 v31, 26, v31
	v_readlane_b32 s7, v253, 28
	s_add_u32 s24, s4, s6
	v_add_u32_e32 v31, v25, v31
	s_addc_u32 s25, s5, s7
	v_lshlrev_b32_e32 v30, 3, v57
	v_ashrrev_i32_e32 v58, 6, v31
	v_and_b32_e32 v31, 0xc0, v31
	s_add_u32 s6, s24, 0xd100000
	v_and_b32_e32 v30, -16, v30
	v_sub_u32_e32 v25, v25, v31
	s_addc_u32 s7, s25, 0
	s_add_u32 s6, s6, s101
	s_addc_u32 s7, s7, 0
	v_readlane_b32 s22, v253, 30
	v_add_u32_e32 v30, v58, v30
	v_lshlrev_b32_e32 v59, 5, v57
	v_ashrrev_i16_sdwa v25, v176, sext(v25) dst_sel:DWORD dst_unused:UNUSED_PAD src0_sel:DWORD src1_sel:BYTE_0
	s_add_u32 s12, s12, s22
	v_and_b32_e32 v60, 32, v59
	v_bfe_i32 v59, v25, 0, 16
	v_lshlrev_b32_e32 v25, 1, v30
	v_lshrrev_b32_e32 v31, 2, v30
	v_and_b32_e32 v61, 3, v58
	s_mov_b32 s22, 0x1fffe0
	v_and_b32_e32 v25, 24, v25
	v_and_b32_e32 v31, 4, v31
	v_and_or_b32 v61, v30, s22, v61
	v_or3_b32 v25, v61, v31, v25
	v_add_lshl_u32 v31, v60, v59, 1
	v_add_u32_e32 v24, 0x2000, v24
	v_lshl_add_u32 v128, v30, 11, v31
	v_lshl_add_u32 v30, v25, 11, v31
	v_ashrrev_i32_e32 v25, 31, v24
	v_lshrrev_b32_e32 v25, 22, v25
	v_add_u32_e32 v25, v24, v25
	v_ashrrev_i32_e32 v60, 10, v25
	v_mul_i32_i24_e32 v25, 0x400, v60
	v_sub_u32_e32 v24, v24, v25
	v_lshrrev_b32_e32 v25, 4, v24
	v_bitop3_b32 v24, v25, v24, 32 bitop3:0x6c
	v_ashrrev_i32_e32 v31, 31, v24
	v_lshrrev_b32_e32 v31, 26, v31
	v_add_u32_e32 v31, v24, v31
	v_lshlrev_b32_e32 v25, 3, v60
	v_ashrrev_i32_e32 v61, 6, v31
	v_and_b32_e32 v31, 0xc0, v31
	v_and_b32_e32 v25, -16, v25
	v_sub_u32_e32 v24, v24, v31
	v_add_u32_e32 v25, v61, v25
	v_lshlrev_b32_e32 v62, 5, v60
	v_ashrrev_i16_sdwa v24, v176, sext(v24) dst_sel:DWORD dst_unused:UNUSED_PAD src0_sel:DWORD src1_sel:BYTE_0
	v_and_b32_e32 v63, 32, v62
	v_bfe_i32 v62, v24, 0, 16
	v_lshlrev_b32_e32 v24, 1, v25
	v_lshrrev_b32_e32 v31, 2, v25
	v_and_b32_e32 v72, 3, v61
	s_addc_u32 s13, s13, 0
	v_and_b32_e32 v24, 24, v24
	v_and_b32_e32 v31, 4, v31
	v_and_or_b32 v72, v25, s22, v72
	s_add_u32 s12, s12, 0x3100000
	v_or3_b32 v24, v72, v31, v24
	v_add_lshl_u32 v31, v63, v62, 1
	s_addc_u32 s13, s13, 0
	s_add_u32 s12, s12, s101
	s_addc_u32 s13, s13, 0
	v_lshl_add_u32 v130, v25, 11, v31
	v_lshl_add_u32 v132, v24, 11, v31
	s_lshl_b32 s21, s21, 10
	v_lshlrev_b64 v[24:25], 12, v[26:27]
	v_lshl_add_u64 v[24:25], v[28:29], 0, v[24:25]
	s_add_i32 s22, s21, 0
	v_lshl_add_u64 v[24:25], v[24:25], 0, v[136:137]
	s_add_i32 m0, s22, 0x10000
	global_load_dwordx4 v[72:75], v[24:25], off offset:16
	global_load_dwordx4 v[76:79], v[24:25], off
	s_add_i32 s23, s22, 0x2000
	global_load_lds_dwordx4 v30, s[12:13]
	s_add_i32 m0, s22, 0x12000
	s_add_u32 s26, s24, 0xd140000
	global_load_lds_dwordx4 v132, s[12:13]
	s_mov_b32 m0, s22
	s_addc_u32 s27, s25, 0
	s_add_u32 s26, s26, s101
	s_addc_u32 s27, s27, 0
	global_load_lds_dwordx4 v128, s[6:7]
	s_mov_b32 m0, s23
	s_add_i32 s24, s22, 0x4000
	global_load_lds_dwordx4 v130, s[6:7]
	s_mov_b32 m0, s24
	s_add_i32 s25, s22, 0x6000
	global_load_lds_dwordx4 v128, s[26:27]
	s_mov_b32 m0, s25
	v_mov_b32_e32 v136, v30
	global_load_lds_dwordx4 v130, s[26:27]
	v_mov_b32_e32 v133, v137
	v_mov_b32_e32 v129, v137
	v_mov_b32_e32 v131, v137
	v_lshl_add_u64 v[30:31], s[12:13], 0, v[136:137]
	v_lshl_add_u64 v[28:29], s[12:13], 0, v[132:133]
	v_lshl_add_u64 v[26:27], s[6:7], 0, v[128:129]
	s_cmp_lg_u32 s20, 1
	v_lshl_add_u64 v[24:25], s[6:7], 0, v[130:131]
	s_cbranch_scc1 .LBB0_1029
	s_barrier
.LBB0_1029:
	v_and_b32_e32 v142, 15, v56
	v_bfe_u32 v143, v56, 4, 2
	v_or_b32_e32 v63, s16, v142
	v_lshlrev_b32_e32 v80, 4, v143
	v_lshlrev_b32_e32 v81, 6, v63
	s_movk_i32 s26, 0x3c0
	v_lshlrev_b32_e32 v63, 2, v63
	v_and_or_b32 v81, v81, s26, v80
	s_lshl_b32 s20, s20, 13
	v_and_b32_e32 v63, 32, v63
	v_lshlrev_b32_e32 v56, 2, v56
	v_bitop3_b32 v63, v81, s20, v63 bitop3:0xde
	v_lshl_or_b32 v80, v142, 6, v80
	s_lshl_b32 s20, s19, 12
	v_and_b32_e32 v56, 32, v56
	s_add_i32 m0, s22, 0x18000
	v_lshl_add_u64 v[30:31], v[30:31], 0, s[88:89]
	v_bitop3_b32 v144, v80, s20, v56 bitop3:0xde
	s_waitcnt vmcnt(2)
	s_barrier
	global_load_lds_dwordx4 v[30:31], off
	v_lshl_add_u64 v[28:29], v[28:29], 0, s[88:89]
	s_add_i32 m0, s22, 0x1a000
	s_add_i32 s20, s22, 0x8000
	global_load_lds_dwordx4 v[28:29], off
	v_lshl_add_u64 v[26:27], v[26:27], 0, s[88:89]
	s_mov_b32 m0, s20
	s_add_i32 s26, s22, 0xa000
	global_load_lds_dwordx4 v[26:27], off
	v_lshl_add_u64 v[24:25], v[24:25], 0, s[88:89]
	s_mov_b32 m0, s26
	v_readlane_b32 s28, v253, 27
	global_load_lds_dwordx4 v[24:25], off
	v_lshlrev_b32_e32 v24, 14, v57
	v_readlane_b32 s29, v253, 28
	s_add_u32 s27, s4, s28
	v_and_b32_e32 v24, 0xffff8000, v24
	s_addc_u32 s28, s5, s29
	v_readlane_b32 s29, v253, 26
	v_lshl_add_u32 v24, v58, 11, v24
	v_and_b32_e32 v25, 1, v57
	s_add_u32 s4, s4, s29
	v_readlane_b32 s29, v253, 29
	v_lshl_or_b32 v24, v25, 6, v24
	s_addc_u32 s5, s5, s29
	v_lshl_add_u32 v24, v59, 1, v24
	v_mov_b32_e32 v25, v137
	v_lshl_add_u64 v[134:135], s[4:5], 0, v[24:25]
	v_lshlrev_b32_e32 v24, 14, v60
	v_and_b32_e32 v24, 0xffff8000, v24
	v_lshl_add_u32 v24, v61, 11, v24
	v_and_b32_e32 v25, 1, v60
	v_lshl_or_b32 v24, v25, 6, v24
	v_lshl_add_u32 v24, v62, 1, v24
	v_mov_b32_e32 v25, v137
	v_lshl_add_u64 v[140:141], s[4:5], 0, v[24:25]
	v_readlane_b32 s4, v253, 31
	s_add_u32 s2, s2, s4
	v_readlane_b32 s4, v253, 32
	s_waitcnt vmcnt(4)
	s_addc_u32 s3, s3, s4
	s_add_u32 s14, s2, s14
	v_mov_b32_e32 v80, 0
	s_addc_u32 s15, s3, s15
	s_mov_b32 s29, -2
	s_mov_b64 s[2:3], 0
	s_mov_b32 s2, s101
	v_add_u32_e32 v145, 0, v63
	v_mov_b32_e32 v81, v80
	v_mov_b32_e32 v82, v80
	v_mov_b32_e32 v83, v80
	v_mov_b32_e32 v84, v80
	v_mov_b32_e32 v85, v80
	v_mov_b32_e32 v86, v80
	v_mov_b32_e32 v87, v80
	v_mov_b32_e32 v88, v80
	v_mov_b32_e32 v89, v80
	v_mov_b32_e32 v90, v80
	v_mov_b32_e32 v91, v80
	v_mov_b32_e32 v92, v80
	v_mov_b32_e32 v93, v80
	v_mov_b32_e32 v94, v80
	v_mov_b32_e32 v95, v80
	v_mov_b32_e32 v96, v80
	v_mov_b32_e32 v97, v80
	v_mov_b32_e32 v98, v80
	v_mov_b32_e32 v99, v80
	v_mov_b32_e32 v100, v80
	v_mov_b32_e32 v101, v80
	v_mov_b32_e32 v102, v80
	v_mov_b32_e32 v103, v80
	v_mov_b32_e32 v104, v80
	v_mov_b32_e32 v105, v80
	v_mov_b32_e32 v106, v80
	v_mov_b32_e32 v107, v80
	v_mov_b32_e32 v108, v80
	v_mov_b32_e32 v109, v80
	v_mov_b32_e32 v110, v80
	v_mov_b32_e32 v111, v80
	v_mov_b32_e32 v112, v80
	v_mov_b32_e32 v113, v80
	v_mov_b32_e32 v114, v80
	v_mov_b32_e32 v115, v80
	v_mov_b32_e32 v116, v80
	v_mov_b32_e32 v117, v80
	v_mov_b32_e32 v118, v80
	v_mov_b32_e32 v119, v80
	v_mov_b32_e32 v56, v80
	v_mov_b32_e32 v57, v80
	v_mov_b32_e32 v58, v80
	v_mov_b32_e32 v59, v80
	v_mov_b32_e32 v60, v80
	v_mov_b32_e32 v61, v80
	v_mov_b32_e32 v62, v80
	v_mov_b32_e32 v63, v80
	v_mov_b32_e32 v28, v80
	v_mov_b32_e32 v29, v80
	v_mov_b32_e32 v30, v80
	v_mov_b32_e32 v31, v80
	v_mov_b32_e32 v24, v80
	v_mov_b32_e32 v25, v80
	v_mov_b32_e32 v26, v80
	v_mov_b32_e32 v27, v80
	v_mov_b32_e32 v120, v80
	v_mov_b32_e32 v121, v80
	v_mov_b32_e32 v122, v80
	v_mov_b32_e32 v123, v80
	v_mov_b32_e32 v124, v80
	v_mov_b32_e32 v125, v80
	v_mov_b32_e32 v126, v80
	v_mov_b32_e32 v127, v80
	s_cmp_lg_u32 s22, 0
	s_cbranch_scc1 .Lmy_pw2_done
.Lmy_pw2_poll:
	s_load_dwordx2 vcc, s[74:75], 0xf8
	s_waitcnt lgkmcnt(0)
	s_add_u32 vcc_lo, vcc_lo, s100
	s_addc_u32 vcc_hi, vcc_hi, 0
	s_add_u32 vcc_lo, vcc_lo, 0x1400
	s_addc_u32 vcc_hi, vcc_hi, 0
	global_load_dword v138, v137, vcc sc1
	s_waitcnt vmcnt(0)
	v_cmp_lt_u32_e32 vcc, 7, v138
	s_cbranch_vccnz .Lmy_pw2_ok
	s_sleep 1
	s_branch .Lmy_pw2_poll
.Lmy_pw2_ok:
	buffer_inv sc1
	s_waitcnt vmcnt(0)
.Lmy_pw2_done:
	s_barrier
.LBB0_1030:
	s_add_u32 s4, s27, s2
	s_addc_u32 s5, s28, s3
	s_add_u32 s4, s4, 0xd100100
	s_addc_u32 s5, s5, 0
	s_add_u32 s30, s14, s2
	s_addc_u32 s31, s15, s3
	s_cmpk_eq_i32 s2, 0x700
	s_cselect_b32 s34, 0x800, 0
	s_sub_u32 s4, s4, s34
	s_subb_u32 s5, s5, 0
	s_sub_u32 s30, s30, s34
	s_subb_u32 s31, s31, 0
	s_cmp_eq_u32 s29, 12
	s_cselect_b32 s5, s7, s5
	s_cselect_b32 s4, s6, s4
	s_cselect_b32 s31, s13, s31
	s_cselect_b32 s30, s12, s30
	s_add_i32 s34, 0, 0x10000
	v_add_u32_e32 v138, s34, v144
	ds_read_b128 v[146:149], v138 offset:3072
	ds_read_b128 v[150:153], v138 offset:2048
	ds_read_b128 v[154:157], v138 offset:1024
	ds_read_b128 v[158:161], v138
	v_lshl_add_u64 v[138:139], v[134:135], 0, s[2:3]
	s_add_i32 m0, s22, 0xc000
	ds_read_b128 v[162:165], v145
	ds_read_b128 v[166:169], v145 offset:1024
	ds_read_b128 v[170:173], v145 offset:2048
	ds_read_b128 v[178:181], v145 offset:3072
	ds_read_b128 v[184:187], v145 offset:4096
	ds_read_b128 v[194:197], v145 offset:5120
	ds_read_b128 v[198:201], v145 offset:6144
	ds_read_b128 v[202:205], v145 offset:7168
	global_load_lds_dwordx4 v[138:139], off
	v_lshl_add_u64 v[138:139], v[140:141], 0, s[2:3]
	s_add_i32 m0, s22, 0xe000
	s_nop 0
	global_load_lds_dwordx4 v[138:139], off
	s_waitcnt vmcnt(6)
	s_waitcnt lgkmcnt(0)
	s_barrier
	s_setprio 1
	s_waitcnt lgkmcnt(0)
	v_mfma_f32_16x16x32_bf16 v[124:127], v[158:161], v[162:165], v[124:127]
	v_mfma_f32_16x16x32_bf16 v[120:123], v[150:153], v[162:165], v[120:123]
	v_mfma_f32_16x16x32_bf16 v[24:27], v[158:161], v[170:173], v[24:27]
	v_mfma_f32_16x16x32_bf16 v[28:31], v[150:153], v[170:173], v[28:31]
	v_mfma_f32_16x16x32_bf16 v[60:63], v[158:161], v[184:187], v[60:63]
	v_mfma_f32_16x16x32_bf16 v[56:59], v[150:153], v[184:187], v[56:59]
	v_mfma_f32_16x16x32_bf16 v[116:119], v[158:161], v[198:201], v[116:119]
	v_mfma_f32_16x16x32_bf16 v[112:115], v[150:153], v[198:201], v[112:115]
	v_mfma_f32_16x16x32_bf16 v[124:127], v[154:157], v[166:169], v[124:127]
	v_mfma_f32_16x16x32_bf16 v[120:123], v[146:149], v[166:169], v[120:123]
	v_mfma_f32_16x16x32_bf16 v[24:27], v[154:157], v[178:181], v[24:27]
	v_mfma_f32_16x16x32_bf16 v[28:31], v[146:149], v[178:181], v[28:31]
	v_mfma_f32_16x16x32_bf16 v[60:63], v[154:157], v[194:197], v[60:63]
	v_mfma_f32_16x16x32_bf16 v[56:59], v[146:149], v[194:197], v[56:59]
	v_mfma_f32_16x16x32_bf16 v[116:119], v[154:157], v[202:205], v[116:119]
	v_mfma_f32_16x16x32_bf16 v[112:115], v[146:149], v[202:205], v[112:115]
	s_setprio 0
	s_barrier
	s_add_i32 s34, s34, s21
	v_lshl_add_u64 v[138:139], s[30:31], 0, v[136:137]
	s_mov_b32 m0, s34
	ds_read_b128 v[162:165], v145 offset:16384
	ds_read_b128 v[166:169], v145 offset:17408
	ds_read_b128 v[170:173], v145 offset:18432
	ds_read_b128 v[178:181], v145 offset:19456
	ds_read_b128 v[184:187], v145 offset:20480
	ds_read_b128 v[194:197], v145 offset:21504
	ds_read_b128 v[198:201], v145 offset:22528
	ds_read_b128 v[202:205], v145 offset:23552
	global_load_lds_dwordx4 v[138:139], off
	v_lshl_add_u64 v[174:175], s[30:31], 0, v[132:133]
	s_add_i32 m0, s34, 0x2000
	v_lshl_add_u64 v[182:183], s[4:5], 0, v[128:129]
	global_load_lds_dwordx4 v[174:175], off
	s_mov_b32 m0, s22
	v_lshl_add_u64 v[188:189], s[4:5], 0, v[130:131]
	global_load_lds_dwordx4 v[182:183], off
	s_mov_b32 m0, s23
	s_nop 0
	global_load_lds_dwordx4 v[188:189], off
	s_waitcnt vmcnt(6)
	s_waitcnt lgkmcnt(0)
	s_barrier
	s_setprio 1
	s_waitcnt lgkmcnt(0)
	v_mfma_f32_16x16x32_bf16 v[108:111], v[158:161], v[162:165], v[108:111]
	v_mfma_f32_16x16x32_bf16 v[104:107], v[150:153], v[162:165], v[104:107]
	v_mfma_f32_16x16x32_bf16 v[100:103], v[158:161], v[170:173], v[100:103]
	v_mfma_f32_16x16x32_bf16 v[96:99], v[150:153], v[170:173], v[96:99]
	v_mfma_f32_16x16x32_bf16 v[92:95], v[158:161], v[184:187], v[92:95]
	v_mfma_f32_16x16x32_bf16 v[88:91], v[150:153], v[184:187], v[88:91]
	v_mfma_f32_16x16x32_bf16 v[84:87], v[158:161], v[198:201], v[84:87]
	v_mfma_f32_16x16x32_bf16 v[80:83], v[150:153], v[198:201], v[80:83]
	v_mfma_f32_16x16x32_bf16 v[108:111], v[154:157], v[166:169], v[108:111]
	v_mfma_f32_16x16x32_bf16 v[104:107], v[146:149], v[166:169], v[104:107]
	v_mfma_f32_16x16x32_bf16 v[100:103], v[154:157], v[178:181], v[100:103]
	v_mfma_f32_16x16x32_bf16 v[96:99], v[146:149], v[178:181], v[96:99]
	v_mfma_f32_16x16x32_bf16 v[92:95], v[154:157], v[194:197], v[92:95]
	v_mfma_f32_16x16x32_bf16 v[88:91], v[146:149], v[194:197], v[88:91]
	v_mfma_f32_16x16x32_bf16 v[84:87], v[154:157], v[202:205], v[84:87]
	v_mfma_f32_16x16x32_bf16 v[80:83], v[146:149], v[202:205], v[80:83]
	s_setprio 0
	s_barrier
	s_add_i32 s30, 0, 0x18000
	v_add_u32_e32 v158, s30, v144
	ds_read_b128 v[146:149], v158
	ds_read_b128 v[150:153], v158 offset:1024
	ds_read_b128 v[154:157], v158 offset:2048
	ds_read_b128 v[158:161], v158 offset:3072
	s_add_u32 s4, s4, 0x40000
	s_addc_u32 s5, s5, 0
	s_mov_b32 m0, s24
	v_lshl_add_u64 v[206:207], s[4:5], 0, v[128:129]
	ds_read_b128 v[162:165], v145 offset:32768
	ds_read_b128 v[166:169], v145 offset:33792
	ds_read_b128 v[170:173], v145 offset:34816
	ds_read_b128 v[178:181], v145 offset:35840
	ds_read_b128 v[184:187], v145 offset:36864
	ds_read_b128 v[194:197], v145 offset:37888
	ds_read_b128 v[198:201], v145 offset:38912
	ds_read_b128 v[202:205], v145 offset:39936
	global_load_lds_dwordx4 v[206:207], off
	v_lshl_add_u64 v[206:207], s[4:5], 0, v[130:131]
	s_mov_b32 m0, s25
	s_nop 0
	global_load_lds_dwordx4 v[206:207], off
	s_waitcnt vmcnt(6)
	s_waitcnt lgkmcnt(0)
	s_barrier
	s_setprio 1
	s_waitcnt lgkmcnt(0)
	v_mfma_f32_16x16x32_bf16 v[124:127], v[146:149], v[162:165], v[124:127]
	v_mfma_f32_16x16x32_bf16 v[120:123], v[154:157], v[162:165], v[120:123]
	v_mfma_f32_16x16x32_bf16 v[24:27], v[146:149], v[170:173], v[24:27]
	v_mfma_f32_16x16x32_bf16 v[28:31], v[154:157], v[170:173], v[28:31]
	v_mfma_f32_16x16x32_bf16 v[60:63], v[146:149], v[184:187], v[60:63]
	v_mfma_f32_16x16x32_bf16 v[56:59], v[154:157], v[184:187], v[56:59]
	v_mfma_f32_16x16x32_bf16 v[116:119], v[146:149], v[198:201], v[116:119]
	v_mfma_f32_16x16x32_bf16 v[112:115], v[154:157], v[198:201], v[112:115]
	v_mfma_f32_16x16x32_bf16 v[124:127], v[150:153], v[166:169], v[124:127]
	v_mfma_f32_16x16x32_bf16 v[120:123], v[158:161], v[166:169], v[120:123]
	v_mfma_f32_16x16x32_bf16 v[24:27], v[150:153], v[178:181], v[24:27]
	v_mfma_f32_16x16x32_bf16 v[28:31], v[158:161], v[178:181], v[28:31]
	v_mfma_f32_16x16x32_bf16 v[60:63], v[150:153], v[194:197], v[60:63]
	v_mfma_f32_16x16x32_bf16 v[56:59], v[158:161], v[194:197], v[56:59]
	v_mfma_f32_16x16x32_bf16 v[116:119], v[150:153], v[202:205], v[116:119]
	v_mfma_f32_16x16x32_bf16 v[112:115], v[158:161], v[202:205], v[112:115]
	s_setprio 0
	s_barrier
	s_add_i32 s4, s30, s21
	v_lshl_add_u64 v[138:139], v[138:139], 0, s[88:89]
	s_mov_b32 m0, s4
	ds_read_b128 v[162:165], v145 offset:49152
	ds_read_b128 v[166:169], v145 offset:50176
	ds_read_b128 v[170:173], v145 offset:51200
	ds_read_b128 v[178:181], v145 offset:52224
	ds_read_b128 v[184:187], v145 offset:53248
	ds_read_b128 v[194:197], v145 offset:54272
	ds_read_b128 v[198:201], v145 offset:55296
	ds_read_b128 v[202:205], v145 offset:56320
	global_load_lds_dwordx4 v[138:139], off
	v_lshl_add_u64 v[138:139], v[174:175], 0, s[88:89]
	s_add_i32 m0, s4, 0x2000
	s_nop 0
	global_load_lds_dwordx4 v[138:139], off
	v_lshl_add_u64 v[138:139], v[182:183], 0, s[88:89]
	s_mov_b32 m0, s20
	s_nop 0
	global_load_lds_dwordx4 v[138:139], off
	v_lshl_add_u64 v[138:139], v[188:189], 0, s[88:89]
	s_mov_b32 m0, s26
	s_nop 0
	global_load_lds_dwordx4 v[138:139], off
	s_waitcnt vmcnt(6)
	s_waitcnt lgkmcnt(0)
	s_barrier
	s_setprio 1
	s_waitcnt lgkmcnt(0)
	v_mfma_f32_16x16x32_bf16 v[108:111], v[146:149], v[162:165], v[108:111]
	v_mfma_f32_16x16x32_bf16 v[104:107], v[154:157], v[162:165], v[104:107]
	v_mfma_f32_16x16x32_bf16 v[100:103], v[146:149], v[170:173], v[100:103]
	v_mfma_f32_16x16x32_bf16 v[96:99], v[154:157], v[170:173], v[96:99]
	v_mfma_f32_16x16x32_bf16 v[92:95], v[146:149], v[184:187], v[92:95]
	v_mfma_f32_16x16x32_bf16 v[88:91], v[154:157], v[184:187], v[88:91]
	v_mfma_f32_16x16x32_bf16 v[84:87], v[146:149], v[198:201], v[84:87]
	v_mfma_f32_16x16x32_bf16 v[80:83], v[154:157], v[198:201], v[80:83]
	v_mfma_f32_16x16x32_bf16 v[108:111], v[150:153], v[166:169], v[108:111]
	v_mfma_f32_16x16x32_bf16 v[104:107], v[158:161], v[166:169], v[104:107]
	v_mfma_f32_16x16x32_bf16 v[100:103], v[150:153], v[178:181], v[100:103]
	v_mfma_f32_16x16x32_bf16 v[96:99], v[158:161], v[178:181], v[96:99]
	v_mfma_f32_16x16x32_bf16 v[92:95], v[150:153], v[194:197], v[92:95]
	v_mfma_f32_16x16x32_bf16 v[88:91], v[158:161], v[194:197], v[88:91]
	v_mfma_f32_16x16x32_bf16 v[84:87], v[150:153], v[202:205], v[84:87]
	v_mfma_f32_16x16x32_bf16 v[80:83], v[158:161], v[202:205], v[80:83]
	s_setprio 0
	s_barrier
	s_add_i32 s29, s29, 2
	s_add_u32 s2, s2, 0x100
	s_and_b32 s2, s2, 0x7ff
	s_cmp_gt_u32 s29, 13
	s_cbranch_scc0 .LBB0_1030
	s_nop 0
	s_nop 0
	s_nop 0
	s_nop 0
	s_nop 0
	s_nop 0
	s_nop 0
	s_nop 0
	s_nop 0
	s_nop 0
	s_nop 0
	s_nop 0
	s_nop 0
	s_nop 0
	s_nop 0
	s_cmpk_lt_u32 s17, 0x100
	s_cbranch_scc0 .LBB0_1033
	s_barrier
